# P12 prompt row pass (executed copy): non-temporal loads and stores
# speedup vs baseline: 1.0072x; 1.0027x over previous
; __device__ __forceinline__ f32x4 up4(u32x2 w) { return (f32x4){bf_lo(w.x), bf_hi(w.x), bf_lo(w.y), bf_hi(w.y)}; }
; template <bool DRYR = false>
; __device__ __forceinline__ void row_pass2(const Args& a, int row_lo, int row_hi, int gw, int NGW, int lane) {
;     ...
;     for (int r0 = row_lo + 2 * gw; r0 < row_hi; r0 += 2 * NGW) {
;         f32x4 xv[2][4]; u32x2 fv[2][4]; float rs[2];
; #pragma unroll
;         for (int r = 0; r < 2; ++r) { const int row = (r0 + r < row_hi) ? r0 + r : r0; rs[r] = rss[row];
;             const f32x4* xo = (const f32x4*)(XO + (size_t)row * DM) + lane; const u32x2* fr = (const u32x2*)(F + (size_t)row * DM) + lane;
; #pragma unroll
;             for (int j = 0; j < 4; ++j) { xv[r][j] = xo[64 * j]; fv[r][j] = fr[64 * j]; } }
; #pragma unroll
;         for (int r = 0; r < 2; ++r) { const int row = r0 + r; if (row >= row_hi) break;
;             const float rstd = rsqrtf(rs[r] * (1.f / DM) + EPS); f32x4* xo = (f32x4*)(XO + (size_t)row * DM) + lane;
; #pragma unroll
;             for (int j = 0; j < 4; ++j) { const f32x4 o = xv[r][j] + up4(fv[r][j]) * rstd * gp[j]; if (!DRYR || o[0] == 123.456f) xo[64 * j] = o; } }
;     }
.LBB0_1417:
	s_add_i32 s5, s0, 1
	s_cmpk_lt_i32 s5, 0x4000
	s_cselect_b32 s20, s5, s0
	s_ashr_i32 s21, s20, 31
	s_lshl_b64 s[22:23], s[20:21], 2
	s_add_u32 s22, s8, s22
	s_waitcnt vmcnt(8)
	v_lshl_add_u64 v[16:17], s[54:55], 0, v[38:39]
	s_addc_u32 s23, s9, s23
	s_lshl_b64 s[24:25], s[20:21], 12
	s_lshl_b64 s[20:21], s[20:21], 11
	v_add_co_u32_e32 v16, vcc, s1, v16
	s_add_u32 s26, s54, s18
	s_nop 0
	v_addc_co_u32_e32 v17, vcc, 0, v17, vcc
	s_addc_u32 s27, s55, s19
	v_lshl_add_u64 v[74:75], v[32:33], 0, s[24:25]
	global_load_dwordx2 v[66:67], v[16:17], off offset:1536 nt
	global_load_dwordx2 v[68:69], v[16:17], off offset:1024 nt
	global_load_dwordx2 v[70:71], v[16:17], off nt
	global_load_dwordx2 v[72:73], v[16:17], off offset:512 nt
	global_load_dword v81, v145, s[26:27]
	global_load_dword v49, v145, s[22:23]
	global_load_dwordx4 v[50:53], v[36:37], off offset:-3072 nt
	global_load_dwordx4 v[54:57], v[36:37], off offset:-4096 nt
	global_load_dwordx4 v[58:61], v[36:37], off offset:-1024 nt
	global_load_dwordx4 v[62:65], v[36:37], off offset:-2048 nt
	v_lshl_add_u64 v[76:77], v[34:35], 0, s[20:21]
	global_load_dwordx4 v[28:31], v[74:75], off nt
	global_load_dwordx4 v[24:27], v[74:75], off offset:1024 nt
	s_waitcnt lgkmcnt(0)
	global_load_dwordx4 v[20:23], v[74:75], off offset:2048 nt
	global_load_dwordx4 v[16:19], v[74:75], off offset:3072 nt
	global_load_dwordx2 v[46:47], v[76:77], off nt
	global_load_dwordx2 v[44:45], v[76:77], off offset:512 nt
	global_load_dwordx2 v[42:43], v[76:77], off offset:1024 nt
	global_load_dwordx2 v[40:41], v[76:77], off offset:1536 nt
	s_cmpk_gt_i32 s5, 0x3fff
	s_waitcnt vmcnt(13)
	v_fmamk_f32 v81, v81, 0x3a800000, v48
	v_mul_f32_e32 v82, 0x4b800000, v81
	v_cmp_gt_f32_e32 vcc, s3, v81
	v_lshlrev_b32_e32 v74, 16, v70
	v_and_b32_e32 v75, 0xffff0000, v70
	v_cndmask_b32_e32 v81, v81, v82, vcc
	v_rsq_f32_e32 v82, v81
	v_lshlrev_b32_e32 v70, 16, v71
	v_and_b32_e32 v71, 0xffff0000, v71
	v_lshlrev_b32_e32 v76, 16, v72
	v_mul_f32_e32 v83, 0x45800000, v82
	v_cndmask_b32_e32 v82, v82, v83, vcc
	v_and_b32_e32 v77, 0xffff0000, v72
	v_lshlrev_b32_e32 v72, 16, v73
	v_and_b32_e32 v73, 0xffff0000, v73
	v_lshlrev_b32_e32 v78, 16, v68
	v_and_b32_e32 v79, 0xffff0000, v68
	v_lshlrev_b32_e32 v68, 16, v69
	v_and_b32_e32 v69, 0xffff0000, v69
	v_lshlrev_b32_e32 v80, 16, v66
	v_and_b32_e32 v81, 0xffff0000, v66
	v_lshlrev_b32_e32 v66, 16, v67
	v_and_b32_e32 v67, 0xffff0000, v67
	v_pk_mul_f32 v[74:75], v[82:83], v[74:75] op_sel_hi:[0,1]
	v_pk_mul_f32 v[70:71], v[82:83], v[70:71] op_sel_hi:[0,1]
	v_pk_mul_f32 v[76:77], v[82:83], v[76:77] op_sel_hi:[0,1]
	v_pk_mul_f32 v[72:73], v[82:83], v[72:73] op_sel_hi:[0,1]
	v_pk_mul_f32 v[78:79], v[82:83], v[78:79] op_sel_hi:[0,1]
	v_pk_mul_f32 v[68:69], v[82:83], v[68:69] op_sel_hi:[0,1]
	v_pk_mul_f32 v[80:81], v[82:83], v[80:81] op_sel_hi:[0,1]
	v_pk_mul_f32 v[66:67], v[82:83], v[66:67] op_sel_hi:[0,1]
	s_waitcnt vmcnt(10)
	v_pk_fma_f32 v[56:57], v[2:3], v[70:71], v[56:57]
	v_pk_fma_f32 v[54:55], v[0:1], v[74:75], v[54:55]
	v_pk_fma_f32 v[52:53], v[6:7], v[72:73], v[52:53]
	v_pk_fma_f32 v[50:51], v[4:5], v[76:77], v[50:51]
	s_waitcnt vmcnt(8)
	v_pk_fma_f32 v[64:65], v[10:11], v[68:69], v[64:65]
	v_pk_fma_f32 v[62:63], v[8:9], v[78:79], v[62:63]
	v_pk_fma_f32 v[60:61], v[14:15], v[66:67], v[60:61]
	v_pk_fma_f32 v[58:59], v[12:13], v[80:81], v[58:59]
	global_store_dwordx4 v[36:37], v[54:57], off offset:-4096 nt
	global_store_dwordx4 v[36:37], v[50:53], off offset:-3072 nt
	global_store_dwordx4 v[36:37], v[62:65], off offset:-2048 nt
	global_store_dwordx4 v[36:37], v[58:61], off offset:-1024 nt
	s_cbranch_scc1 .LBB0_1416
	v_fmamk_f32 v49, v49, 0x3a800000, v48
	v_mul_f32_e32 v50, 0x4b800000, v49
	v_cmp_gt_f32_e32 vcc, s3, v49
	s_waitcnt vmcnt(7)
	v_and_b32_e32 v51, 0xffff0000, v46
	v_lshlrev_b32_e32 v52, 16, v47
	v_cndmask_b32_e32 v49, v49, v50, vcc
	v_rsq_f32_e32 v49, v49
	v_lshlrev_b32_e32 v50, 16, v46
	v_and_b32_e32 v53, 0xffff0000, v47
	v_mul_f32_e32 v46, 0x45800000, v49
	v_cndmask_b32_e32 v46, v49, v46, vcc
	v_pk_mul_f32 v[50:51], v[46:47], v[50:51] op_sel_hi:[0,1]
	v_pk_mul_f32 v[52:53], v[46:47], v[52:53] op_sel_hi:[0,1]
	v_pk_fma_f32 v[30:31], v[2:3], v[52:53], v[30:31]
	v_pk_fma_f32 v[28:29], v[0:1], v[50:51], v[28:29]
	global_store_dwordx4 v[36:37], v[28:31], off nt
	s_waitcnt vmcnt(7)
	s_nop 0
	v_lshlrev_b32_e32 v28, 16, v44
	v_and_b32_e32 v29, 0xffff0000, v44
	v_lshlrev_b32_e32 v30, 16, v45
	v_and_b32_e32 v31, 0xffff0000, v45
	v_pk_mul_f32 v[28:29], v[46:47], v[28:29] op_sel_hi:[0,1]
	v_pk_mul_f32 v[30:31], v[46:47], v[30:31] op_sel_hi:[0,1]
	v_pk_fma_f32 v[26:27], v[6:7], v[30:31], v[26:27]
	v_pk_fma_f32 v[24:25], v[4:5], v[28:29], v[24:25]
	global_store_dwordx4 v[36:37], v[24:27], off offset:1024 nt
	s_waitcnt vmcnt(7)
	s_nop 0
	v_lshlrev_b32_e32 v24, 16, v42
	v_and_b32_e32 v25, 0xffff0000, v42
	v_lshlrev_b32_e32 v26, 16, v43
	v_and_b32_e32 v27, 0xffff0000, v43
	v_pk_mul_f32 v[24:25], v[46:47], v[24:25] op_sel_hi:[0,1]
	v_pk_mul_f32 v[26:27], v[46:47], v[26:27] op_sel_hi:[0,1]
	v_pk_fma_f32 v[22:23], v[10:11], v[26:27], v[22:23]
	v_pk_fma_f32 v[20:21], v[8:9], v[24:25], v[20:21]
	global_store_dwordx4 v[36:37], v[20:23], off offset:2048 nt
	s_waitcnt vmcnt(7)
	s_nop 0
	v_lshlrev_b32_e32 v20, 16, v40
	v_and_b32_e32 v21, 0xffff0000, v40
	v_lshlrev_b32_e32 v22, 16, v41
	v_and_b32_e32 v23, 0xffff0000, v41
	v_pk_mul_f32 v[20:21], v[46:47], v[20:21] op_sel_hi:[0,1]
	v_pk_mul_f32 v[22:23], v[46:47], v[22:23] op_sel_hi:[0,1]
	v_pk_fma_f32 v[18:19], v[14:15], v[22:23], v[18:19]
	v_pk_fma_f32 v[16:17], v[12:13], v[20:21], v[16:17]
	global_store_dwordx4 v[36:37], v[16:19], off offset:3072 nt
	s_branch .LBB0_1416
